# grid barrier: thread 0 reads its three barrier-state words with LDS reads issued together (was three serialized flat loads)
# baseline (speedup 1.0000x reference)
; __device__ __forceinline__ unsigned xb_ld(unsigned* p) { return __hip_atomic_load(p, __ATOMIC_RELAXED, __HIP_MEMORY_SCOPE_AGENT); }
; __device__ __forceinline__ unsigned xb_add(unsigned* p, unsigned v) { return __hip_atomic_fetch_add(p, v, __ATOMIC_RELAXED, __HIP_MEMORY_SCOPE_AGENT); }
; __device__ __forceinline__ void grid_barrier(unsigned* bar, volatile unsigned* st) {
;   asm volatile("s_waitcnt vmcnt(0)" ::: "memory");
;   __syncthreads();
;   if (threadIdx.x == 0) {
;     __builtin_amdgcn_s_waitcnt(0);
;     const unsigned x = st[2], nloc = st[0], nx = st[1];
;     const unsigned old = xb_add(&bar[XB_XSUB(x)], 1u);
;     const unsigned gen = old / nloc;
;     if (old + 1u == (gen + 1u) * nloc) {
;       __builtin_amdgcn_fence(__ATOMIC_RELEASE, "agent");
;       asm volatile("s_waitcnt vmcnt(0)" ::: "memory");
;       const unsigned og = xb_add(&bar[XB_TOP], 1u);
;       const unsigned tg = og / nx;
;       if (og + 1u == (tg + 1u) * nx) xb_add(&bar[XB_TOPGEN], 1u);
;       else { while (xb_ld(&bar[XB_TOPGEN]) == tg) __builtin_amdgcn_s_sleep(1); }
;       __builtin_amdgcn_fence(__ATOMIC_ACQUIRE, "agent");
;       xb_add(&bar[XB_XGEN(x)], 1u);
;       asm volatile("s_waitcnt vmcnt(0)" ::: "memory");
;     } else {
;       while (xb_ld(&bar[XB_XGEN(x)]) == gen) __builtin_amdgcn_s_sleep(1);
.LBB0_882:
	v_mov_b32_e32 v6, 0x24000
	s_waitcnt vmcnt(0) expcnt(0) lgkmcnt(0)
	ds_read_b32 v2, v6 offset:8
	ds_read_b32 v4, v6
	ds_read_b32 v0, v6 offset:4
	s_waitcnt lgkmcnt(0)
	v_readlane_b32 s6, v253, 3
	v_readlane_b32 s7, v253, 4
	s_waitcnt lgkmcnt(0)
	v_lshlrev_b32_e32 v1, 6, v2
	v_add_u32_e32 v200, 0x500, v1
	v_lshl_add_u64 v[2:3], v[200:201], 2, s[6:7]
	global_atomic_add v3, v[2:3], v238, off sc0
	v_add_u32_e32 v200, 0x900, v1
	v_cvt_f32_u32_e32 v2, v4
	v_sub_u32_e32 v5, 0, v4
	v_rcp_iflag_f32_e32 v2, v2
	s_nop 0
	v_mul_f32_e32 v2, 0x4f7ffffe, v2
	v_cvt_u32_f32_e32 v2, v2
	v_mul_lo_u32 v5, v5, v2
	v_mul_hi_u32 v5, v2, v5
	v_add_u32_e32 v2, v2, v5
	s_waitcnt vmcnt(0)
	v_mul_hi_u32 v2, v3, v2
	v_mul_lo_u32 v5, v2, v4
	v_sub_u32_e32 v5, v3, v5
	v_cmp_ge_u32_e32 vcc, v5, v4
	v_add_u32_e32 v6, 1, v2
	v_add_u32_e32 v3, 1, v3
	v_cndmask_b32_e32 v2, v2, v6, vcc
	v_sub_u32_e32 v6, v5, v4
	v_cndmask_b32_e32 v5, v5, v6, vcc
	v_cmp_ge_u32_e32 vcc, v5, v4
	v_add_u32_e32 v5, 1, v2
	s_nop 0
	v_cndmask_b32_e32 v2, v2, v5, vcc
	v_mad_u64_u32 v[4:5], s[6:7], v4, v2, v[4:5]
	v_cmp_ne_u32_e32 vcc, v3, v4
	s_and_saveexec_b64 s[6:7], vcc
	s_xor_b64 s[6:7], exec, s[6:7]
	s_cbranch_execz .LBB0_887
	v_readlane_b32 s8, v253, 3
	v_readlane_b32 s9, v253, 4
	s_nop 1
	v_lshl_add_u64 v[0:1], v[200:201], 2, s[8:9]
	global_load_dword v3, v[0:1], off sc1
	s_waitcnt vmcnt(0)
	v_cmp_eq_u32_e32 vcc, v3, v2
	s_and_saveexec_b64 s[8:9], vcc
	s_cbranch_execz .LBB0_886
	s_mov_b64 s[10:11], 0
